# v23
# speedup vs baseline: 1.0010x; 1.0010x over previous
; __device__ __forceinline__ void attn_item_fast(const u16* __restrict__ Qg, const u16* __restrict__ Kg, const u16* __restrict__ Vtg,
;                                                u16* __restrict__ Og, const int L, char* smem, const int tid) {
;     ...
;   f32x16 O[2][2];
; #pragma unroll
;   for (int a = 0; a < 2; ++a)
; #pragma unroll
;     for (int b = 0; b < 2; ++b)
; #pragma unroll
;       for (int i = 0; i < 16; ++i) O[a][b][i] = 0.f;
;   float l0 = 0.f, l1 = 0.f;
;   const int lrow = tid >> 3, lch = tid & 7;
;   const int lsc = lch ^ ((lrow >> 1) & 7);
;   const unsigned koff = (unsigned)(lrow * 256 + lsc * 8) * 2u;
;   const unsigned voff = (unsigned)(lrow * L + lsc * 8) * 2u;
;   const unsigned ldsK = (unsigned)(uintptr_t)smem + (unsigned)__builtin_amdgcn_readfirstlane(w) * 1024u;
;   const unsigned ldsV = ldsK + 16384u;
;   char* Ks = smem; char* Vs = smem + 16384;
;   const int sw = (r32 >> 1) & 7;
; #pragma unroll
;   for (int qb = 0; qb < 2; ++qb)
; #pragma unroll
;     for (int kk = 0; kk < 4; ++kk) asm volatile("" : "+v"(qf[qb][kk]));
;   glds16(koff, (const char*)Kg, ldsK); glds16(voff, (const char*)Vtg, ldsV);
;   asm volatile("s_waitcnt vmcnt(0)" ::: "memory");
;   __syncthreads();
;   bf16x8 kf[4], vf[4], P0[2], P1[2];
; #pragma unroll
;   for (int i = 0; i < 4; ++i)
; #pragma unroll
;     for (int e = 0; e < 8; ++e) vf[i][e] = 0;
; #pragma unroll
;   for (int i = 0; i < 2; ++i)
; #pragma unroll
;     for (int e = 0; e < 8; ++e) { P0[i][e] = 0; P1[i][e] = 0; }
;     ...
;   for (int t = 0; t < NT; ++t) {
;     const int cur = (t & 1) * 8192;
;     const char* Kb = Ks + cur; const char* Vb = Vs + cur;
;     if (t + 1 < NT) {
;       const char* kb_ = (const char*)Kg + (size_t)(t + 1) * (64 * 256 * 2);
;       const char* vb_ = (const char*)Vtg + (size_t)(t + 1) * 128;
;       glds16(koff, kb_, ldsK + (unsigned)(cur ^ 8192)); glds16(voff, vb_, ldsV + (unsigned)(cur ^ 8192));
;     }
;     ld_kf<0>(kf, Kb, r32, hi, sw);
;     ATT_PV(vf, P0, P1);
;     ld_vf<0>(vf, Vb, r32, hi, sw);
;     ATT_QK(S0, S1, kf);
;     ld_kf<1>(kf, Kb, r32, hi, sw);
.LBB0_92:
	s_add_u32 s34, s34, 0x8000
	s_addc_u32 s35, s35, 0
	s_add_u32 s38, s38, 0x80
	v_mov_b32_e32 v130, 0
	v_mov_b32_e32 v2, 0
	s_addc_u32 s39, s39, 0
	s_mov_b32 s53, 0
	v_mov_b32_e32 v70, 0
	v_mov_b32_e32 v71, 0
	v_mov_b32_e32 v72, 0
	v_mov_b32_e32 v73, 0
	v_mov_b32_e32 v74, 0
	v_mov_b32_e32 v75, 0
	v_mov_b32_e32 v76, 0
	v_mov_b32_e32 v77, 0
	v_mov_b32_e32 v66, 0
	v_mov_b32_e32 v67, 0
	v_mov_b32_e32 v68, 0
	v_mov_b32_e32 v69, 0
	v_mov_b32_e32 v78, 0
	v_mov_b32_e32 v79, 0
	v_mov_b32_e32 v80, 0
	v_mov_b32_e32 v81, 0
	v_mov_b32_e32 v3, v2
	v_mov_b32_e32 v4, v2
	v_mov_b32_e32 v5, v2
	v_mov_b32_e32 v6, v2
	v_mov_b32_e32 v7, v2
	v_mov_b32_e32 v8, v2
	v_mov_b32_e32 v9, v2
	v_mov_b32_e32 v10, v2
	v_mov_b32_e32 v11, v2
	v_mov_b32_e32 v12, v2
	v_mov_b32_e32 v13, v2
	v_mov_b32_e32 v14, v2
	v_mov_b32_e32 v15, v2
	v_mov_b32_e32 v16, v2
	v_mov_b32_e32 v17, v2
	v_mov_b32_e32 v34, v2
	v_mov_b32_e32 v35, v2
	v_mov_b32_e32 v36, v2
	v_mov_b32_e32 v37, v2
	v_mov_b32_e32 v38, v2
	v_mov_b32_e32 v39, v2
	v_mov_b32_e32 v40, v2
	v_mov_b32_e32 v41, v2
	v_mov_b32_e32 v42, v2
	v_mov_b32_e32 v43, v2
	v_mov_b32_e32 v44, v2
	v_mov_b32_e32 v45, v2
	v_mov_b32_e32 v46, v2
	v_mov_b32_e32 v47, v2
	v_mov_b32_e32 v48, v2
	v_mov_b32_e32 v49, v2
	v_mov_b32_e32 v18, v2
	v_mov_b32_e32 v19, v2
	v_mov_b32_e32 v20, v2
	v_mov_b32_e32 v21, v2
	v_mov_b32_e32 v22, v2
	v_mov_b32_e32 v23, v2
	v_mov_b32_e32 v24, v2
	v_mov_b32_e32 v25, v2
	v_mov_b32_e32 v26, v2
	v_mov_b32_e32 v27, v2
	v_mov_b32_e32 v28, v2
	v_mov_b32_e32 v29, v2
	v_mov_b32_e32 v30, v2
	v_mov_b32_e32 v31, v2
	v_mov_b32_e32 v32, v2
	v_mov_b32_e32 v33, v2
	v_mov_b32_e32 v50, v2
	v_mov_b32_e32 v51, v2
	v_mov_b32_e32 v52, v2
	v_mov_b32_e32 v53, v2
	v_mov_b32_e32 v54, v2
	v_mov_b32_e32 v55, v2
	v_mov_b32_e32 v56, v2
	v_mov_b32_e32 v57, v2
	v_mov_b32_e32 v58, v2
	v_mov_b32_e32 v59, v2
	v_mov_b32_e32 v60, v2
	v_mov_b32_e32 v61, v2
	v_mov_b32_e32 v62, v2
	v_mov_b32_e32 v63, v2
	v_mov_b32_e32 v64, v2
	v_mov_b32_e32 v65, v2
	v_mov_b32_e32 v131, v130
	v_mov_b32_e32 v132, v130
	v_mov_b32_e32 v133, v130
	v_mov_b32_e32 v138, v130
	v_mov_b32_e32 v139, v130
	v_mov_b32_e32 v140, v130
	v_mov_b32_e32 v141, v130
	v_mov_b32_e32 v134, v130
	v_mov_b32_e32 v135, v130
	v_mov_b32_e32 v136, v130
	v_mov_b32_e32 v137, v130
	v_mov_b32_e32 v142, v130
	v_mov_b32_e32 v143, v130
	v_mov_b32_e32 v144, v130
	v_mov_b32_e32 v145, v130
	v_mov_b32_e32 v172, v2
	v_mov_b32_e32 v173, v2
	v_mov_b32_e32 v206, 0
	v_mov_b32_e32 v207, 0
	v_mov_b32_e32 v208, 0
	v_mov_b32_e32 v209, 0
	v_mov_b32_e32 v210, 0
	v_mov_b32_e32 v211, 0
	v_mov_b32_e32 v212, 0
	v_mov_b32_e32 v213, 0
	v_mov_b32_e32 v214, 0
	v_mov_b32_e32 v215, 0
	v_mov_b32_e32 v216, 0
	v_mov_b32_e32 v217, 0
	v_mov_b32_e32 v218, 0
	v_mov_b32_e32 v219, 0
	v_mov_b32_e32 v220, 0
	v_mov_b32_e32 v221, 0
	v_mov_b32_e32 v248, 0
	v_mov_b32_e32 v249, 0
.LBB0_93:
	s_and_b32 s3, s53, 0x2000
	s_xor_b32 s13, s3, 0x2000
	s_add_i32 s15, s13, s49
	s_add_i32 s13, s13, s48
	s_mov_b32 s52, m0
	s_mov_b32 m0, s13
	s_nop 0
	global_load_lds_dwordx4 v179, s[34:35]
	s_mov_b32 m0, s52
	v_add_u32_e32 v82, s3, v181
	s_mov_b32 s13, m0
	s_mov_b32 m0, s15
	s_nop 0
	global_load_lds_dwordx4 v180, s[38:39]
	s_mov_b32 m0, s13
	v_add_u32_e32 v188, v82, v182
	ds_read_b128 v[146:149], v188
	v_mfma_f32_32x32x16_bf16 v[50:65], v[142:145], v[206:209], v[50:65]
	v_add_u32_e32 v189, v82, v183
	ds_read_b128 v[150:153], v189
	v_add_u32_e32 v186, v82, v184
	v_add_u32_e32 v187, v82, v185
	ds_read_b128 v[154:157], v186
	ds_read_b128 v[158:161], v187
	v_add_f32_e32 v172, v172, v248
	v_add_f32_e32 v173, v173, v249
	v_mfma_f32_32x32x16_bf16 v[18:33], v[142:145], v[214:217], v[18:33]
	v_mfma_f32_32x32x16_bf16 v[34:49], v[138:141], v[206:209], v[34:49]
	v_mfma_f32_32x32x16_bf16 v[2:17], v[138:141], v[214:217], v[2:17]
	s_waitcnt lgkmcnt(3)
	v_mfma_f32_32x32x16_bf16 v[66:81], v[146:149], v[126:129], 0
	v_mfma_f32_32x32x16_bf16 v[82:97], v[146:149], v[118:121], 0
	s_waitcnt lgkmcnt(2)
	v_mfma_f32_32x32x16_bf16 v[66:81], v[150:153], v[122:125], v[66:81]
	v_mfma_f32_32x32x16_bf16 v[82:97], v[150:153], v[114:117], v[82:97]
	s_waitcnt lgkmcnt(1)
	v_mfma_f32_32x32x16_bf16 v[66:81], v[154:157], v[110:113], v[66:81]
	v_mfma_f32_32x32x16_bf16 v[82:97], v[154:157], v[106:109], v[82:97]
	s_waitcnt lgkmcnt(0)
	v_mfma_f32_32x32x16_bf16 v[66:81], v[158:161], v[98:101], v[66:81]
	v_mfma_f32_32x32x16_bf16 v[82:97], v[158:161], v[102:105], v[82:97]
	ds_read_b128 v[146:149], v188 offset:4096
	ds_read_b128 v[150:153], v189 offset:4096
	ds_read_b128 v[154:157], v186 offset:4096
	ds_read_b128 v[158:161], v187 offset:4096
	v_mfma_f32_32x32x16_bf16 v[50:65], v[134:137], v[210:213], v[50:65]
	v_mfma_f32_32x32x16_bf16 v[18:33], v[134:137], v[218:221], v[18:33]
	v_mfma_f32_32x32x16_bf16 v[34:49], v[130:133], v[210:213], v[34:49]
	v_mfma_f32_32x32x16_bf16 v[2:17], v[130:133], v[218:221], v[2:17]
	ds_read_b128 v[142:145], v188 offset:16384
	ds_read_b128 v[134:137], v189 offset:16384
	ds_read_b128 v[138:141], v188 offset:20480
	ds_read_b128 v[130:133], v189 offset:20480
	s_setprio 0
	s_barrier
; #define ATT_QK(S0_, S1_, kf_) do { \
;     _Pragma("unroll") for (int i_ = 0; i_ < 16; ++i_) { S0_[i_] = 0.f; S1_[i_] = 0.f; } \
;     _Pragma("unroll") for (int kk_ = 0; kk_ < 4; ++kk_) { \
;       S0_ = __builtin_amdgcn_mfma_f32_32x32x16_bf16(kf_[kk_], qf[0][kk_], S0_, 0, 0, 0); \
;       S1_ = __builtin_amdgcn_mfma_f32_32x32x16_bf16(kf_[kk_], qf[1][kk_], S1_, 0, 0, 0); } } while (0)
; #define ATT_PV(vf_, P0_, P1_) do { \
;     _Pragma("unroll") for (int c_ = 0; c_ < 2; ++c_) \
;     _Pragma("unroll") for (int db_ = 0; db_ < 2; ++db_) { \
;       O[db_][0] = __builtin_amdgcn_mfma_f32_32x32x16_bf16(vf_[db_ * 2 + c_], P0_[c_], O[db_][0], 0, 0, 0); \
;       O[db_][1] = __builtin_amdgcn_mfma_f32_32x32x16_bf16(vf_[db_ * 2 + c_], P1_[c_], O[db_][1], 0, 0, 0); } } while (0)
; #define WBAR() do { __builtin_amdgcn_sched_barrier(0); __builtin_amdgcn_s_barrier(); __builtin_amdgcn_sched_barrier(0); } while (0)
; __device__ __forceinline__ void exp_pack(f32x16& s, float& l, bf16x8& p0, bf16x8& p1) {
; #pragma unroll
;   for (int i = 0; i < 16; ++i) s[i] = __builtin_amdgcn_exp2f(s[i]);
;   const float a0 = (s[0] + s[1]) + (s[2] + s[3]), a1 = (s[4] + s[5]) + (s[6] + s[7]);
;   const float a2 = (s[8] + s[9]) + (s[10] + s[11]), a3 = (s[12] + s[13]) + (s[14] + s[15]);
;   l += (a0 + a1) + (a2 + a3);
;   p0 = pack8(s, 0); p1 = pack8(s, 8);
; }
; __device__ __forceinline__ void attn_item_fast(const u16* __restrict__ Qg, const u16* __restrict__ Kg, const u16* __restrict__ Vtg,
;                                                u16* __restrict__ Og, const int L, char* smem, const int tid) {
;     ...
;     WBAR();
;     exp_pack(S0, l0, P0[0], P0[1]); exp_pack(S1, l1, P1[0], P1[1]);
;     WBAR();
;     ATT_PV(vf, P0, P1);
;     ld_vf<1>(vf, Vb, r32, hi, sw);
;     ATT_QK(S0, S1, kf);
;     asm volatile("s_waitcnt vmcnt(0) lgkmcnt(0)" ::: "memory");
;     WBAR();
;     exp_pack(S0, l0, P0[0], P0[1]); exp_pack(S1, l1, P1[0], P1[1]);
;     WBAR();
	v_exp_f32_e32 v66, v66
	v_exp_f32_e32 v67, v67
	v_exp_f32_e32 v68, v68
	v_exp_f32_e32 v69, v69
	v_exp_f32_e32 v82, v82
	v_exp_f32_e32 v83, v83
	v_exp_f32_e32 v84, v84
	v_exp_f32_e32 v85, v85
	v_exp_f32_e32 v70, v70
	v_exp_f32_e32 v71, v71
	v_exp_f32_e32 v72, v72
	v_exp_f32_e32 v73, v73
	v_exp_f32_e32 v86, v86
	v_exp_f32_e32 v87, v87
	v_exp_f32_e32 v88, v88
	v_exp_f32_e32 v89, v89
	v_exp_f32_e32 v74, v74
	v_exp_f32_e32 v75, v75
	v_exp_f32_e32 v76, v76
	v_exp_f32_e32 v77, v77
	v_exp_f32_e32 v90, v90
	v_exp_f32_e32 v91, v91
	v_exp_f32_e32 v92, v92
	v_exp_f32_e32 v93, v93
	v_exp_f32_e32 v78, v78
	v_exp_f32_e32 v79, v79
	v_exp_f32_e32 v80, v80
	v_exp_f32_e32 v81, v81
	v_exp_f32_e32 v94, v94
	v_exp_f32_e32 v95, v95
	v_exp_f32_e32 v96, v96
	v_exp_f32_e32 v97, v97
	v_add_f32_e32 v238, v82, v83
	v_add_f32_e32 v242, v66, v67
	v_add_f32_e32 v239, v84, v85
	v_add_f32_e32 v243, v68, v69
	v_add_f32_e32 v238, v238, v239
	v_add_f32_e32 v242, v242, v243
	v_add_f32_e32 v239, v86, v87
	v_add_f32_e32 v243, v70, v71
	v_add_f32_e32 v240, v88, v89
	v_add_f32_e32 v244, v72, v73
	v_add_f32_e32 v239, v239, v240
	v_add_f32_e32 v243, v243, v244
	v_add_f32_e32 v238, v238, v239
	v_add_f32_e32 v242, v242, v243
	v_add_f32_e32 v239, v90, v91
	v_add_f32_e32 v243, v74, v75
	v_add_f32_e32 v240, v92, v93
	v_add_f32_e32 v244, v76, v77
	v_add_f32_e32 v239, v239, v240
	v_add_f32_e32 v243, v243, v244
	v_add_f32_e32 v240, v94, v95
	v_add_f32_e32 v244, v78, v79
	v_add_f32_e32 v241, v96, v97
	v_add_f32_e32 v245, v80, v81
	v_add_f32_e32 v240, v240, v241
	v_add_f32_e32 v244, v244, v245
	v_add_f32_e32 v239, v239, v240
	v_add_f32_e32 v243, v243, v244
	v_add_f32_e32 v246, v238, v239
	v_add_f32_e32 v247, v242, v243
	v_cvt_pk_bf16_f32 v206, v82, v83
	v_cvt_pk_bf16_f32 v214, v66, v67
	v_cvt_pk_bf16_f32 v207, v84, v85
	v_cvt_pk_bf16_f32 v215, v68, v69
	v_cvt_pk_bf16_f32 v208, v86, v87
	v_cvt_pk_bf16_f32 v216, v70, v71
	v_cvt_pk_bf16_f32 v209, v88, v89
	v_cvt_pk_bf16_f32 v217, v72, v73
	v_cvt_pk_bf16_f32 v210, v90, v91
	v_cvt_pk_bf16_f32 v218, v74, v75
	v_cvt_pk_bf16_f32 v211, v92, v93
	v_cvt_pk_bf16_f32 v219, v76, v77
	v_cvt_pk_bf16_f32 v212, v94, v95
	v_cvt_pk_bf16_f32 v220, v78, v79
	v_cvt_pk_bf16_f32 v213, v96, v97
	v_cvt_pk_bf16_f32 v221, v80, v81
	s_barrier
	s_setprio 1
	s_waitcnt lgkmcnt(3)
	v_mfma_f32_32x32x16_bf16 v[50:65], v[142:145], v[206:209], v[50:65]
	v_add_f32_e32 v172, v172, v246
	v_add_f32_e32 v173, v173, v247
	v_mfma_f32_32x32x16_bf16 v[18:33], v[142:145], v[214:217], v[18:33]
	s_waitcnt lgkmcnt(1)
	v_mfma_f32_32x32x16_bf16 v[34:49], v[138:141], v[206:209], v[34:49]
	v_mfma_f32_32x32x16_bf16 v[2:17], v[138:141], v[214:217], v[2:17]
	v_mfma_f32_32x32x16_bf16 v[66:81], v[146:149], v[126:129], 0
	v_mfma_f32_32x32x16_bf16 v[82:97], v[146:149], v[118:121], 0
	v_mfma_f32_32x32x16_bf16 v[66:81], v[150:153], v[122:125], v[66:81]
	v_mfma_f32_32x32x16_bf16 v[82:97], v[150:153], v[114:117], v[82:97]
	v_mfma_f32_32x32x16_bf16 v[66:81], v[154:157], v[110:113], v[66:81]
	v_mfma_f32_32x32x16_bf16 v[82:97], v[154:157], v[106:109], v[82:97]
	v_mfma_f32_32x32x16_bf16 v[66:81], v[158:161], v[98:101], v[66:81]
	v_mfma_f32_32x32x16_bf16 v[82:97], v[158:161], v[102:105], v[82:97]
	s_waitcnt lgkmcnt(0)
	v_mfma_f32_32x32x16_bf16 v[50:65], v[134:137], v[210:213], v[50:65]
	v_mfma_f32_32x32x16_bf16 v[18:33], v[134:137], v[218:221], v[18:33]
	v_mfma_f32_32x32x16_bf16 v[34:49], v[130:133], v[210:213], v[34:49]
	v_mfma_f32_32x32x16_bf16 v[2:17], v[130:133], v[218:221], v[2:17]
	ds_read_b128 v[142:145], v186 offset:16384
	ds_read_b128 v[138:141], v186 offset:20480
	ds_read_b128 v[134:137], v187 offset:16384
	ds_read_b128 v[130:133], v187 offset:20480
	s_waitcnt vmcnt(0) lgkmcnt(0)
	s_setprio 0
	s_barrier
	v_exp_f32_e32 v66, v66
	v_exp_f32_e32 v67, v67
	v_exp_f32_e32 v68, v68
	v_exp_f32_e32 v69, v69
	v_exp_f32_e32 v82, v82
	v_exp_f32_e32 v83, v83
	v_exp_f32_e32 v84, v84
	v_exp_f32_e32 v85, v85
	v_exp_f32_e32 v70, v70
	v_exp_f32_e32 v71, v71
	v_exp_f32_e32 v72, v72
	v_exp_f32_e32 v73, v73
	v_exp_f32_e32 v86, v86
	v_exp_f32_e32 v87, v87
	v_exp_f32_e32 v88, v88
	v_exp_f32_e32 v89, v89
	v_exp_f32_e32 v74, v74
	v_exp_f32_e32 v75, v75
	v_exp_f32_e32 v76, v76
	v_exp_f32_e32 v77, v77
	v_exp_f32_e32 v90, v90
	v_exp_f32_e32 v91, v91
	v_exp_f32_e32 v92, v92
	v_exp_f32_e32 v93, v93
	v_exp_f32_e32 v78, v78
	v_exp_f32_e32 v79, v79
	v_exp_f32_e32 v80, v80
	v_exp_f32_e32 v81, v81
	v_exp_f32_e32 v94, v94
	v_exp_f32_e32 v95, v95
	v_exp_f32_e32 v96, v96
	v_exp_f32_e32 v97, v97
	v_add_f32_e32 v238, v82, v83
	v_add_f32_e32 v242, v66, v67
	v_add_f32_e32 v239, v84, v85
	v_add_f32_e32 v243, v68, v69
	v_add_f32_e32 v238, v238, v239
	v_add_f32_e32 v242, v242, v243
	v_add_f32_e32 v239, v86, v87
	v_add_f32_e32 v243, v70, v71
	v_add_f32_e32 v240, v88, v89
	v_add_f32_e32 v244, v72, v73
	v_add_f32_e32 v239, v239, v240
	v_add_f32_e32 v243, v243, v244
	v_add_f32_e32 v238, v238, v239
	v_add_f32_e32 v242, v242, v243
	v_add_f32_e32 v239, v90, v91
	v_add_f32_e32 v243, v74, v75
	v_add_f32_e32 v240, v92, v93
	v_add_f32_e32 v244, v76, v77
	v_add_f32_e32 v239, v239, v240
	v_add_f32_e32 v243, v243, v244
	v_add_f32_e32 v240, v94, v95
	v_add_f32_e32 v244, v78, v79
	v_add_f32_e32 v241, v96, v97
	v_add_f32_e32 v245, v80, v81
	v_add_f32_e32 v240, v240, v241
	v_add_f32_e32 v244, v244, v245
	v_add_f32_e32 v239, v239, v240
	v_add_f32_e32 v243, v243, v244
	v_add_f32_e32 v248, v238, v239
	v_add_f32_e32 v249, v242, v243
	v_cvt_pk_bf16_f32 v206, v82, v83
	v_cvt_pk_bf16_f32 v214, v66, v67
	v_cvt_pk_bf16_f32 v207, v84, v85
	v_cvt_pk_bf16_f32 v215, v68, v69
	v_cvt_pk_bf16_f32 v208, v86, v87
	v_cvt_pk_bf16_f32 v216, v70, v71
	v_cvt_pk_bf16_f32 v209, v88, v89
	v_cvt_pk_bf16_f32 v217, v72, v73
	v_cvt_pk_bf16_f32 v210, v90, v91
	v_cvt_pk_bf16_f32 v218, v74, v75
	v_cvt_pk_bf16_f32 v211, v92, v93
	v_cvt_pk_bf16_f32 v219, v76, v77
	v_cvt_pk_bf16_f32 v212, v94, v95
	v_cvt_pk_bf16_f32 v220, v78, v79
	v_cvt_pk_bf16_f32 v213, v96, v97
	v_cvt_pk_bf16_f32 v221, v80, v81
	s_barrier
; #define ATT_QK(S0_, S1_, kf_) do { \
;     _Pragma("unroll") for (int i_ = 0; i_ < 16; ++i_) { S0_[i_] = 0.f; S1_[i_] = 0.f; } \
;     _Pragma("unroll") for (int kk_ = 0; kk_ < 4; ++kk_) { \
;       S0_ = __builtin_amdgcn_mfma_f32_32x32x16_bf16(kf_[kk_], qf[0][kk_], S0_, 0, 0, 0); \
;       S1_ = __builtin_amdgcn_mfma_f32_32x32x16_bf16(kf_[kk_], qf[1][kk_], S1_, 0, 0, 0); } } while (0)
; #define ATT_PV(vf_, P0_, P1_) do { \
;     _Pragma("unroll") for (int c_ = 0; c_ < 2; ++c_) \
;     _Pragma("unroll") for (int db_ = 0; db_ < 2; ++db_) { \
;       O[db_][0] = __builtin_amdgcn_mfma_f32_32x32x16_bf16(vf_[db_ * 2 + c_], P0_[c_], O[db_][0], 0, 0, 0); \
;       O[db_][1] = __builtin_amdgcn_mfma_f32_32x32x16_bf16(vf_[db_ * 2 + c_], P1_[c_], O[db_][1], 0, 0, 0); } } while (0)
; #define WBAR() do { __builtin_amdgcn_sched_barrier(0); __builtin_amdgcn_s_barrier(); __builtin_amdgcn_sched_barrier(0); } while (0)
; __device__ __forceinline__ void attn_item_fast(const u16* __restrict__ Qg, const u16* __restrict__ Kg, const u16* __restrict__ Vtg,
;                                                u16* __restrict__ Og, const int L, char* smem, const int tid) {
;     ...
;   for (int t = 0; t < NT; ++t) {
;     const int cur = (t & 1) * 8192;
;     const char* Kb = Ks + cur; const char* Vb = Vs + cur;
;     if (t + 1 < NT) {
;       const char* kb_ = (const char*)Kg + (size_t)(t + 1) * (64 * 256 * 2);
;       const char* vb_ = (const char*)Vtg + (size_t)(t + 1) * 128;
;       glds16(koff, kb_, ldsK + (unsigned)(cur ^ 8192)); glds16(voff, vb_, ldsV + (unsigned)(cur ^ 8192));
;     }
;     ld_kf<0>(kf, Kb, r32, hi, sw);
;     ATT_PV(vf, P0, P1);
;     ld_vf<0>(vf, Vb, r32, hi, sw);
;     ATT_QK(S0, S1, kf);
;     ld_kf<1>(kf, Kb, r32, hi, sw);
;     WBAR();
;     exp_pack(S0, l0, P0[0], P0[1]); exp_pack(S1, l1, P1[0], P1[1]);
;     WBAR();
;     ATT_PV(vf, P0, P1);
;     ld_vf<1>(vf, Vb, r32, hi, sw);
;     ATT_QK(S0, S1, kf);
;     asm volatile("s_waitcnt vmcnt(0) lgkmcnt(0)" ::: "memory");
;     WBAR();
;     exp_pack(S0, l0, P0[0], P0[1]); exp_pack(S1, l1, P1[0], P1[1]);
;     WBAR();
;   }
;   if (half == 0) WBAR();
	s_setprio 1
	s_addk_i32 s53, 0x2000
	s_add_u32 s34, s34, 0x8000
	s_addc_u32 s35, s35, 0
	s_add_u32 s38, s38, 0x80
	s_addc_u32 s39, s39, 0
	s_cmp_eq_u32 s53, 0x1fe000
	s_cbranch_scc0 .LBB0_93
	s_setprio 0
	v_add_f32_e32 v172, v172, v248
	v_add_f32_e32 v173, v173, v249
	v_mov_b32_e32 v74, v206
	v_mov_b32_e32 v75, v207
	v_mov_b32_e32 v76, v208
	v_mov_b32_e32 v77, v209
	v_mov_b32_e32 v70, v210
	v_mov_b32_e32 v71, v211
	v_mov_b32_e32 v72, v212
	v_mov_b32_e32 v73, v213
	v_mov_b32_e32 v78, v214
	v_mov_b32_e32 v79, v215
	v_mov_b32_e32 v80, v216
	v_mov_b32_e32 v81, v217
	v_mov_b32_e32 v66, v218
	v_mov_b32_e32 v67, v219
	v_mov_b32_e32 v68, v220
	v_mov_b32_e32 v69, v221
	v_add_u32_e32 v205, v181, v182
	ds_read_b128 v[146:149], v205 offset:8192
	s_waitcnt lgkmcnt(4)
	v_mfma_f32_32x32x16_bf16 v[50:65], v[142:145], v[74:77], v[50:65]
	v_add_u32_e32 v222, v181, v183
	ds_read_b128 v[150:153], v222 offset:8192
	v_add_u32_e32 v234, v181, v184
	ds_read_b128 v[154:157], v234 offset:8192
	v_add_u32_e32 v235, v181, v185
	ds_read_b128 v[158:161], v235 offset:8192
	ds_read_b128 v[186:189], v205 offset:24576
	ds_read_b128 v[206:209], v222 offset:24576
	ds_read_b128 v[210:213], v205 offset:28672
	ds_read_b128 v[214:217], v222 offset:28672
	v_mfma_f32_32x32x16_bf16 v[18:33], v[142:145], v[78:81], v[18:33]
	ds_read_b128 v[218:221], v205 offset:12288
	ds_read_b128 v[222:225], v222 offset:12288
	ds_read_b128 v[226:229], v234 offset:12288
	ds_read_b128 v[230:233], v235 offset:12288
	s_waitcnt lgkmcnt(14)
	v_mfma_f32_32x32x16_bf16 v[34:49], v[138:141], v[74:77], v[34:49]
	v_mfma_f32_32x32x16_bf16 v[2:17], v[138:141], v[78:81], v[2:17]
	s_waitcnt lgkmcnt(13)
	v_mfma_f32_32x32x16_bf16 v[50:65], v[134:137], v[70:73], v[50:65]
	v_mfma_f32_32x32x16_bf16 v[18:33], v[134:137], v[66:69], v[18:33]
	s_waitcnt lgkmcnt(12)
	v_mfma_f32_32x32x16_bf16 v[34:49], v[130:133], v[70:73], v[34:49]
	v_mfma_f32_32x32x16_bf16 v[2:17], v[130:133], v[66:69], v[2:17]
	s_waitcnt lgkmcnt(11)
	v_mfma_f32_32x32x16_bf16 v[82:97], v[146:149], v[118:121], 0
	v_mfma_f32_32x32x16_bf16 v[66:81], v[146:149], v[126:129], 0
	s_waitcnt lgkmcnt(10)
	v_mfma_f32_32x32x16_bf16 v[82:97], v[150:153], v[114:117], v[82:97]
	v_mfma_f32_32x32x16_bf16 v[66:81], v[150:153], v[122:125], v[66:81]
	s_waitcnt lgkmcnt(9)
	v_mfma_f32_32x32x16_bf16 v[82:97], v[154:157], v[106:109], v[82:97]
	v_mfma_f32_32x32x16_bf16 v[66:81], v[154:157], v[110:113], v[66:81]
	s_waitcnt lgkmcnt(8)
	v_mfma_f32_32x32x16_bf16 v[82:97], v[158:161], v[102:105], v[82:97]
	v_mfma_f32_32x32x16_bf16 v[66:81], v[158:161], v[98:101], v[66:81]
	s_barrier
	s_nop 9
	v_exp_f32_e32 v138, v82
	v_exp_f32_e32 v144, v83
	v_exp_f32_e32 v132, v84
	v_exp_f32_e32 v139, v85
	v_exp_f32_e32 v133, v86
	v_exp_f32_e32 v140, v87
	v_exp_f32_e32 v141, v88
	v_exp_f32_e32 v145, v89
	v_exp_f32_e32 v134, v90
	v_exp_f32_e32 v142, v91
	v_exp_f32_e32 v130, v92
	v_exp_f32_e32 v135, v93
	v_exp_f32_e32 v131, v94
	v_exp_f32_e32 v136, v95
	v_exp_f32_e32 v137, v96
	v_exp_f32_e32 v143, v97
	v_exp_f32_e32 v146, v66
	v_exp_f32_e32 v147, v67
	v_exp_f32_e32 v148, v68
	v_exp_f32_e32 v151, v69
	v_exp_f32_e32 v149, v70
	v_exp_f32_e32 v152, v71
	v_exp_f32_e32 v153, v72
	v_exp_f32_e32 v157, v73
	v_exp_f32_e32 v150, v74
	v_exp_f32_e32 v154, v75
	v_exp_f32_e32 v155, v76
	v_exp_f32_e32 v158, v77
	v_exp_f32_e32 v156, v78
	v_exp_f32_e32 v159, v79
	v_exp_f32_e32 v160, v80
	v_exp_f32_e32 v161, v81
	v_cvt_pk_bf16_f32 v82, v138, v144
	v_cvt_pk_bf16_f32 v83, v132, v139
	v_cvt_pk_bf16_f32 v84, v133, v140
	v_cvt_pk_bf16_f32 v85, v141, v145
	v_cvt_pk_bf16_f32 v86, v134, v142
	v_cvt_pk_bf16_f32 v87, v130, v135
	v_cvt_pk_bf16_f32 v88, v131, v136
	v_cvt_pk_bf16_f32 v89, v137, v143
	v_cvt_pk_bf16_f32 v66, v146, v147
	v_cvt_pk_bf16_f32 v67, v148, v151
	v_cvt_pk_bf16_f32 v68, v149, v152
	v_cvt_pk_bf16_f32 v69, v153, v157
	v_cvt_pk_bf16_f32 v70, v150, v154
	v_cvt_pk_bf16_f32 v71, v155, v158
	v_cvt_pk_bf16_f32 v72, v156, v159
	v_cvt_pk_bf16_f32 v73, v160, v161
	s_barrier
	s_waitcnt lgkmcnt(7)
	v_mfma_f32_32x32x16_bf16 v[50:65], v[186:189], v[82:85], v[50:65]
	v_mfma_f32_32x32x16_bf16 v[18:33], v[186:189], v[66:69], v[18:33]
	s_waitcnt lgkmcnt(5)
	v_mfma_f32_32x32x16_bf16 v[34:49], v[210:213], v[82:85], v[34:49]
	v_mfma_f32_32x32x16_bf16 v[2:17], v[210:213], v[66:69], v[2:17]
	v_mfma_f32_32x32x16_bf16 v[50:65], v[206:209], v[86:89], v[50:65]
	v_mfma_f32_32x32x16_bf16 v[18:33], v[206:209], v[70:73], v[18:33]
	s_waitcnt lgkmcnt(4)
	v_mfma_f32_32x32x16_bf16 v[34:49], v[214:217], v[86:89], v[34:49]
	v_mfma_f32_32x32x16_bf16 v[2:17], v[214:217], v[70:73], v[2:17]
	s_waitcnt lgkmcnt(3)
	v_mfma_f32_32x32x16_bf16 v[82:97], v[218:221], v[118:121], 0
	v_mfma_f32_32x32x16_bf16 v[66:81], v[218:221], v[126:129], 0
	s_waitcnt lgkmcnt(2)
	v_mfma_f32_32x32x16_bf16 v[82:97], v[222:225], v[114:117], v[82:97]
	v_mfma_f32_32x32x16_bf16 v[66:81], v[222:225], v[122:125], v[66:81]
	s_waitcnt lgkmcnt(1)
	v_mfma_f32_32x32x16_bf16 v[82:97], v[226:229], v[106:109], v[82:97]
	v_mfma_f32_32x32x16_bf16 v[66:81], v[226:229], v[110:113], v[66:81]
	s_waitcnt lgkmcnt(0)
	v_mfma_f32_32x32x16_bf16 v[82:97], v[230:233], v[102:105], v[82:97]
	ds_read_b128 v[114:117], v234 offset:24576
	ds_read_b128 v[110:113], v234 offset:28672
	ds_read_b128 v[106:109], v235 offset:24576
	ds_read_b128 v[102:105], v235 offset:28672
	s_waitcnt vmcnt(0) lgkmcnt(0)
	v_mfma_f32_32x32x16_bf16 v[66:81], v[230:233], v[98:101], v[66:81]
	s_barrier
	s_nop 5
	v_exp_f32_e32 v98, v82
	v_exp_f32_e32 v99, v83
	v_exp_f32_e32 v100, v84
	v_exp_f32_e32 v119, v85
	v_exp_f32_e32 v101, v86
	v_exp_f32_e32 v120, v87
	v_exp_f32_e32 v121, v88
	v_exp_f32_e32 v122, v89
	v_exp_f32_e32 v90, v90
	v_exp_f32_e32 v91, v91
	v_exp_f32_e32 v92, v92
	v_exp_f32_e32 v118, v93
	v_exp_f32_e32 v93, v94
	v_exp_f32_e32 v94, v95
	v_exp_f32_e32 v95, v96
	v_exp_f32_e32 v96, v97
	v_exp_f32_e32 v186, v66
	v_exp_f32_e32 v187, v67
	v_exp_f32_e32 v188, v68
	v_exp_f32_e32 v189, v69
	v_exp_f32_e32 v97, v70
	v_exp_f32_e32 v124, v71
	v_exp_f32_e32 v125, v72
	v_exp_f32_e32 v128, v73
	v_exp_f32_e32 v123, v74
	v_exp_f32_e32 v126, v75
	v_exp_f32_e32 v127, v76
	v_exp_f32_e32 v129, v77
	v_exp_f32_e32 v74, v78
	v_exp_f32_e32 v75, v79
	v_exp_f32_e32 v76, v80
	v_exp_f32_e32 v77, v81
	v_cvt_pk_bf16_f32 v86, v98, v99
	v_cvt_pk_bf16_f32 v87, v100, v119
	v_cvt_pk_bf16_f32 v88, v101, v120
	v_cvt_pk_bf16_f32 v89, v121, v122
	v_cvt_pk_bf16_f32 v82, v90, v91
	v_cvt_pk_bf16_f32 v83, v92, v118
	v_cvt_pk_bf16_f32 v84, v93, v94
	v_cvt_pk_bf16_f32 v85, v95, v96
	v_cvt_pk_bf16_f32 v70, v186, v187
	v_cvt_pk_bf16_f32 v71, v188, v189
	v_cvt_pk_bf16_f32 v72, v97, v124
	v_cvt_pk_bf16_f32 v73, v125, v128
	v_cvt_pk_bf16_f32 v66, v123, v126
	v_cvt_pk_bf16_f32 v67, v127, v129
	v_cvt_pk_bf16_f32 v68, v74, v75
	v_cvt_pk_bf16_f32 v69, v76, v77
	s_barrier
	s_cmpk_lt_u32 s14, 0x100
	s_cbranch_scc0 .LBB0_89
	s_barrier
	s_branch .LBB0_89

; __device__ __forceinline__ void attn_item_fast(const u16* __restrict__ Qg, const u16* __restrict__ Kg, const u16* __restrict__ Vtg,
;                                                u16* __restrict__ Og, const int L, char* smem, const int tid) {
;     ...
;   f32x16 O[2][2];
; #pragma unroll
;   for (int a = 0; a < 2; ++a)
; #pragma unroll
;     for (int b = 0; b < 2; ++b)
; #pragma unroll
;       for (int i = 0; i < 16; ++i) O[a][b][i] = 0.f;
;   float l0 = 0.f, l1 = 0.f;
;   const int lrow = tid >> 3, lch = tid & 7;
;   const int lsc = lch ^ ((lrow >> 1) & 7);
;   const unsigned koff = (unsigned)(lrow * 256 + lsc * 8) * 2u;
;   const unsigned voff = (unsigned)(lrow * L + lsc * 8) * 2u;
;   const unsigned ldsK = (unsigned)(uintptr_t)smem + (unsigned)__builtin_amdgcn_readfirstlane(w) * 1024u;
;   const unsigned ldsV = ldsK + 16384u;
;   char* Ks = smem; char* Vs = smem + 16384;
;   const int sw = (r32 >> 1) & 7;
; #pragma unroll
;   for (int qb = 0; qb < 2; ++qb)
; #pragma unroll
;     for (int kk = 0; kk < 4; ++kk) asm volatile("" : "+v"(qf[qb][kk]));
;   glds16(koff, (const char*)Kg, ldsK); glds16(voff, (const char*)Vtg, ldsV);
;   asm volatile("s_waitcnt vmcnt(0)" ::: "memory");
;   __syncthreads();
;   bf16x8 kf[4], vf[4], P0[2], P1[2];
; #pragma unroll
;   for (int i = 0; i < 4; ++i)
; #pragma unroll
;     for (int e = 0; e < 8; ++e) vf[i][e] = 0;
; #pragma unroll
;   for (int i = 0; i < 2; ++i)
; #pragma unroll
;     for (int e = 0; e < 8; ++e) { P0[i][e] = 0; P1[i][e] = 0; }
;     ...
;   for (int t = 0; t < NT; ++t) {
;     const int cur = (t & 1) * 8192;
;     const char* Kb = Ks + cur; const char* Vb = Vs + cur;
;     if (t + 1 < NT) {
;       const char* kb_ = (const char*)Kg + (size_t)(t + 1) * (64 * 256 * 2);
;       const char* vb_ = (const char*)Vtg + (size_t)(t + 1) * 128;
;       glds16(koff, kb_, ldsK + (unsigned)(cur ^ 8192)); glds16(voff, vb_, ldsV + (unsigned)(cur ^ 8192));
;     }
;     ld_kf<0>(kf, Kb, r32, hi, sw);
;     ATT_PV(vf, P0, P1);
;     ld_vf<0>(vf, Vb, r32, hi, sw);
;     ATT_QK(S0, S1, kf);
;     ld_kf<1>(kf, Kb, r32, hi, sw);
.LBB0_101:
	s_lshl_b64 s[6:7], s[6:7], 10
	s_add_u32 s10, s10, 0x8000
	s_addc_u32 s11, s11, 0
	s_add_u32 s34, s34, 0x80
	v_mov_b32_e32 v130, 0
	v_mov_b32_e32 v2, 0
	s_addc_u32 s35, s35, 0
	s_mov_b32 s53, 0
	v_mov_b32_e32 v70, 0
	v_mov_b32_e32 v71, 0
	v_mov_b32_e32 v72, 0
	v_mov_b32_e32 v73, 0
	v_mov_b32_e32 v74, 0
	v_mov_b32_e32 v75, 0
	v_mov_b32_e32 v76, 0
	v_mov_b32_e32 v77, 0
	v_mov_b32_e32 v66, 0
	v_mov_b32_e32 v67, 0
	v_mov_b32_e32 v68, 0
	v_mov_b32_e32 v69, 0
	v_mov_b32_e32 v78, 0
	v_mov_b32_e32 v79, 0
	v_mov_b32_e32 v80, 0
	v_mov_b32_e32 v81, 0
	v_mov_b32_e32 v3, v2
	v_mov_b32_e32 v4, v2
	v_mov_b32_e32 v5, v2
	v_mov_b32_e32 v6, v2
	v_mov_b32_e32 v7, v2
	v_mov_b32_e32 v8, v2
	v_mov_b32_e32 v9, v2
	v_mov_b32_e32 v10, v2
	v_mov_b32_e32 v11, v2
	v_mov_b32_e32 v12, v2
	v_mov_b32_e32 v13, v2
	v_mov_b32_e32 v14, v2
	v_mov_b32_e32 v15, v2
	v_mov_b32_e32 v16, v2
	v_mov_b32_e32 v17, v2
	v_mov_b32_e32 v34, v2
	v_mov_b32_e32 v35, v2
	v_mov_b32_e32 v36, v2
	v_mov_b32_e32 v37, v2
	v_mov_b32_e32 v38, v2
	v_mov_b32_e32 v39, v2
	v_mov_b32_e32 v40, v2
	v_mov_b32_e32 v41, v2
	v_mov_b32_e32 v42, v2
	v_mov_b32_e32 v43, v2
	v_mov_b32_e32 v44, v2
	v_mov_b32_e32 v45, v2
	v_mov_b32_e32 v46, v2
	v_mov_b32_e32 v47, v2
	v_mov_b32_e32 v48, v2
	v_mov_b32_e32 v49, v2
	v_mov_b32_e32 v18, v2
	v_mov_b32_e32 v19, v2
	v_mov_b32_e32 v20, v2
	v_mov_b32_e32 v21, v2
	v_mov_b32_e32 v22, v2
	v_mov_b32_e32 v23, v2
	v_mov_b32_e32 v24, v2
	v_mov_b32_e32 v25, v2
	v_mov_b32_e32 v26, v2
	v_mov_b32_e32 v27, v2
	v_mov_b32_e32 v28, v2
	v_mov_b32_e32 v29, v2
	v_mov_b32_e32 v30, v2
	v_mov_b32_e32 v31, v2
	v_mov_b32_e32 v32, v2
	v_mov_b32_e32 v33, v2
	v_mov_b32_e32 v50, v2
	v_mov_b32_e32 v51, v2
	v_mov_b32_e32 v52, v2
	v_mov_b32_e32 v53, v2
	v_mov_b32_e32 v54, v2
	v_mov_b32_e32 v55, v2
	v_mov_b32_e32 v56, v2
	v_mov_b32_e32 v57, v2
	v_mov_b32_e32 v58, v2
	v_mov_b32_e32 v59, v2
	v_mov_b32_e32 v60, v2
	v_mov_b32_e32 v61, v2
	v_mov_b32_e32 v62, v2
	v_mov_b32_e32 v63, v2
	v_mov_b32_e32 v64, v2
	v_mov_b32_e32 v65, v2
	v_mov_b32_e32 v131, v130
	v_mov_b32_e32 v132, v130
	v_mov_b32_e32 v133, v130
	v_mov_b32_e32 v138, v130
	v_mov_b32_e32 v139, v130
	v_mov_b32_e32 v140, v130
	v_mov_b32_e32 v141, v130
	v_mov_b32_e32 v134, v130
	v_mov_b32_e32 v135, v130
	v_mov_b32_e32 v136, v130
	v_mov_b32_e32 v137, v130
	v_mov_b32_e32 v142, v130
	v_mov_b32_e32 v143, v130
	v_mov_b32_e32 v144, v130
	v_mov_b32_e32 v145, v130
	v_mov_b32_e32 v162, v2
	v_mov_b32_e32 v163, v2
	v_mov_b32_e32 v206, 0
	v_mov_b32_e32 v207, 0
	v_mov_b32_e32 v208, 0
	v_mov_b32_e32 v209, 0
	v_mov_b32_e32 v210, 0
	v_mov_b32_e32 v211, 0
	v_mov_b32_e32 v212, 0
	v_mov_b32_e32 v213, 0
	v_mov_b32_e32 v214, 0
	v_mov_b32_e32 v215, 0
	v_mov_b32_e32 v216, 0
	v_mov_b32_e32 v217, 0
	v_mov_b32_e32 v218, 0
	v_mov_b32_e32 v219, 0
	v_mov_b32_e32 v220, 0
	v_mov_b32_e32 v221, 0
	v_mov_b32_e32 v248, 0
	v_mov_b32_e32 v249, 0
.LBB0_102:
	s_and_b32 s3, s53, 0x2000
	s_xor_b32 s13, s3, 0x2000
	s_add_i32 s15, s13, s49
	s_add_i32 s13, s13, s48
	s_mov_b32 s52, m0
	s_mov_b32 m0, s13
	s_nop 0
	global_load_lds_dwordx4 v168, s[10:11]
	s_mov_b32 m0, s52
	v_add_u32_e32 v82, s3, v170
	s_mov_b32 s13, m0
	s_mov_b32 m0, s15
	s_nop 0
	global_load_lds_dwordx4 v169, s[34:35]
	s_mov_b32 m0, s13
	v_add_u32_e32 v178, v82, v171
	ds_read_b128 v[146:149], v178
	v_mfma_f32_32x32x16_bf16 v[50:65], v[142:145], v[206:209], v[50:65]
	v_add_u32_e32 v179, v82, v172
	ds_read_b128 v[150:153], v179
	v_add_u32_e32 v175, v82, v173
	v_add_u32_e32 v176, v82, v174
	ds_read_b128 v[154:157], v175
	ds_read_b128 v[158:161], v176
	v_add_f32_e32 v162, v162, v248
	v_add_f32_e32 v163, v163, v249
	v_mfma_f32_32x32x16_bf16 v[18:33], v[142:145], v[214:217], v[18:33]
	v_mfma_f32_32x32x16_bf16 v[34:49], v[138:141], v[206:209], v[34:49]
	v_mfma_f32_32x32x16_bf16 v[2:17], v[138:141], v[214:217], v[2:17]
	s_waitcnt lgkmcnt(3)
	v_mfma_f32_32x32x16_bf16 v[66:81], v[146:149], v[126:129], 0
	v_mfma_f32_32x32x16_bf16 v[82:97], v[146:149], v[118:121], 0
	s_waitcnt lgkmcnt(2)
	v_mfma_f32_32x32x16_bf16 v[66:81], v[150:153], v[122:125], v[66:81]
	v_mfma_f32_32x32x16_bf16 v[82:97], v[150:153], v[114:117], v[82:97]
	s_waitcnt lgkmcnt(1)
	v_mfma_f32_32x32x16_bf16 v[66:81], v[154:157], v[110:113], v[66:81]
	v_mfma_f32_32x32x16_bf16 v[82:97], v[154:157], v[106:109], v[82:97]
	s_waitcnt lgkmcnt(0)
	v_mfma_f32_32x32x16_bf16 v[66:81], v[158:161], v[98:101], v[66:81]
	v_mfma_f32_32x32x16_bf16 v[82:97], v[158:161], v[102:105], v[82:97]
	ds_read_b128 v[146:149], v178 offset:4096
	ds_read_b128 v[150:153], v179 offset:4096
	ds_read_b128 v[154:157], v175 offset:4096
	ds_read_b128 v[158:161], v176 offset:4096
	v_mfma_f32_32x32x16_bf16 v[50:65], v[134:137], v[210:213], v[50:65]
	v_mfma_f32_32x32x16_bf16 v[18:33], v[134:137], v[218:221], v[18:33]
	v_mfma_f32_32x32x16_bf16 v[34:49], v[130:133], v[210:213], v[34:49]
	v_mfma_f32_32x32x16_bf16 v[2:17], v[130:133], v[218:221], v[2:17]
	ds_read_b128 v[142:145], v178 offset:16384
	ds_read_b128 v[134:137], v179 offset:16384
	ds_read_b128 v[138:141], v178 offset:20480
	ds_read_b128 v[130:133], v179 offset:20480
	s_setprio 0
	s_barrier
; #define ATT_QK(S0_, S1_, kf_) do { \
;     _Pragma("unroll") for (int i_ = 0; i_ < 16; ++i_) { S0_[i_] = 0.f; S1_[i_] = 0.f; } \
;     _Pragma("unroll") for (int kk_ = 0; kk_ < 4; ++kk_) { \
;       S0_ = __builtin_amdgcn_mfma_f32_32x32x16_bf16(kf_[kk_], qf[0][kk_], S0_, 0, 0, 0); \
;       S1_ = __builtin_amdgcn_mfma_f32_32x32x16_bf16(kf_[kk_], qf[1][kk_], S1_, 0, 0, 0); } } while (0)
; #define ATT_PV(vf_, P0_, P1_) do { \
;     _Pragma("unroll") for (int c_ = 0; c_ < 2; ++c_) \
;     _Pragma("unroll") for (int db_ = 0; db_ < 2; ++db_) { \
;       O[db_][0] = __builtin_amdgcn_mfma_f32_32x32x16_bf16(vf_[db_ * 2 + c_], P0_[c_], O[db_][0], 0, 0, 0); \
;       O[db_][1] = __builtin_amdgcn_mfma_f32_32x32x16_bf16(vf_[db_ * 2 + c_], P1_[c_], O[db_][1], 0, 0, 0); } } while (0)
; #define WBAR() do { __builtin_amdgcn_sched_barrier(0); __builtin_amdgcn_s_barrier(); __builtin_amdgcn_sched_barrier(0); } while (0)
; __device__ __forceinline__ void exp_pack(f32x16& s, float& l, bf16x8& p0, bf16x8& p1) {
; #pragma unroll
;   for (int i = 0; i < 16; ++i) s[i] = __builtin_amdgcn_exp2f(s[i]);
;   const float a0 = (s[0] + s[1]) + (s[2] + s[3]), a1 = (s[4] + s[5]) + (s[6] + s[7]);
;   const float a2 = (s[8] + s[9]) + (s[10] + s[11]), a3 = (s[12] + s[13]) + (s[14] + s[15]);
;   l += (a0 + a1) + (a2 + a3);
;   p0 = pack8(s, 0); p1 = pack8(s, 8);
; }
; __device__ __forceinline__ void attn_item_fast(const u16* __restrict__ Qg, const u16* __restrict__ Kg, const u16* __restrict__ Vtg,
;                                                u16* __restrict__ Og, const int L, char* smem, const int tid) {
;     ...
;     WBAR();
;     exp_pack(S0, l0, P0[0], P0[1]); exp_pack(S1, l1, P1[0], P1[1]);
;     WBAR();
;     ATT_PV(vf, P0, P1);
;     ld_vf<1>(vf, Vb, r32, hi, sw);
;     ATT_QK(S0, S1, kf);
;     asm volatile("s_waitcnt vmcnt(0) lgkmcnt(0)" ::: "memory");
;     WBAR();
;     exp_pack(S0, l0, P0[0], P0[1]); exp_pack(S1, l1, P1[0], P1[1]);
;     WBAR();
	v_exp_f32_e32 v66, v66
	v_exp_f32_e32 v67, v67
	v_exp_f32_e32 v68, v68
	v_exp_f32_e32 v69, v69
	v_exp_f32_e32 v82, v82
	v_exp_f32_e32 v83, v83
	v_exp_f32_e32 v84, v84
	v_exp_f32_e32 v85, v85
	v_exp_f32_e32 v70, v70
	v_exp_f32_e32 v71, v71
	v_exp_f32_e32 v72, v72
	v_exp_f32_e32 v73, v73
	v_exp_f32_e32 v86, v86
	v_exp_f32_e32 v87, v87
	v_exp_f32_e32 v88, v88
	v_exp_f32_e32 v89, v89
	v_exp_f32_e32 v74, v74
	v_exp_f32_e32 v75, v75
	v_exp_f32_e32 v76, v76
	v_exp_f32_e32 v77, v77
	v_exp_f32_e32 v90, v90
	v_exp_f32_e32 v91, v91
	v_exp_f32_e32 v92, v92
	v_exp_f32_e32 v93, v93
	v_exp_f32_e32 v78, v78
	v_exp_f32_e32 v79, v79
	v_exp_f32_e32 v80, v80
	v_exp_f32_e32 v81, v81
	v_exp_f32_e32 v94, v94
	v_exp_f32_e32 v95, v95
	v_exp_f32_e32 v96, v96
	v_exp_f32_e32 v97, v97
	v_add_f32_e32 v238, v82, v83
	v_add_f32_e32 v242, v66, v67
	v_add_f32_e32 v239, v84, v85
	v_add_f32_e32 v243, v68, v69
	v_add_f32_e32 v238, v238, v239
	v_add_f32_e32 v242, v242, v243
	v_add_f32_e32 v239, v86, v87
	v_add_f32_e32 v243, v70, v71
	v_add_f32_e32 v240, v88, v89
	v_add_f32_e32 v244, v72, v73
	v_add_f32_e32 v239, v239, v240
	v_add_f32_e32 v243, v243, v244
	v_add_f32_e32 v238, v238, v239
	v_add_f32_e32 v242, v242, v243
	v_add_f32_e32 v239, v90, v91
	v_add_f32_e32 v243, v74, v75
	v_add_f32_e32 v240, v92, v93
	v_add_f32_e32 v244, v76, v77
	v_add_f32_e32 v239, v239, v240
	v_add_f32_e32 v243, v243, v244
	v_add_f32_e32 v240, v94, v95
	v_add_f32_e32 v244, v78, v79
	v_add_f32_e32 v241, v96, v97
	v_add_f32_e32 v245, v80, v81
	v_add_f32_e32 v240, v240, v241
	v_add_f32_e32 v244, v244, v245
	v_add_f32_e32 v239, v239, v240
	v_add_f32_e32 v243, v243, v244
	v_add_f32_e32 v246, v238, v239
	v_add_f32_e32 v247, v242, v243
	v_cvt_pk_bf16_f32 v206, v82, v83
	v_cvt_pk_bf16_f32 v214, v66, v67
	v_cvt_pk_bf16_f32 v207, v84, v85
	v_cvt_pk_bf16_f32 v215, v68, v69
	v_cvt_pk_bf16_f32 v208, v86, v87
	v_cvt_pk_bf16_f32 v216, v70, v71
	v_cvt_pk_bf16_f32 v209, v88, v89
	v_cvt_pk_bf16_f32 v217, v72, v73
	v_cvt_pk_bf16_f32 v210, v90, v91
	v_cvt_pk_bf16_f32 v218, v74, v75
	v_cvt_pk_bf16_f32 v211, v92, v93
	v_cvt_pk_bf16_f32 v219, v76, v77
	v_cvt_pk_bf16_f32 v212, v94, v95
	v_cvt_pk_bf16_f32 v220, v78, v79
	v_cvt_pk_bf16_f32 v213, v96, v97
	v_cvt_pk_bf16_f32 v221, v80, v81
	s_barrier
	s_setprio 1
	s_waitcnt lgkmcnt(3)
	v_mfma_f32_32x32x16_bf16 v[50:65], v[142:145], v[206:209], v[50:65]
	v_add_f32_e32 v162, v162, v246
	v_add_f32_e32 v163, v163, v247
	v_mfma_f32_32x32x16_bf16 v[18:33], v[142:145], v[214:217], v[18:33]
	s_waitcnt lgkmcnt(1)
	v_mfma_f32_32x32x16_bf16 v[34:49], v[138:141], v[206:209], v[34:49]
	v_mfma_f32_32x32x16_bf16 v[2:17], v[138:141], v[214:217], v[2:17]
	v_mfma_f32_32x32x16_bf16 v[66:81], v[146:149], v[126:129], 0
	v_mfma_f32_32x32x16_bf16 v[82:97], v[146:149], v[118:121], 0
	v_mfma_f32_32x32x16_bf16 v[66:81], v[150:153], v[122:125], v[66:81]
	v_mfma_f32_32x32x16_bf16 v[82:97], v[150:153], v[114:117], v[82:97]
	v_mfma_f32_32x32x16_bf16 v[66:81], v[154:157], v[110:113], v[66:81]
	v_mfma_f32_32x32x16_bf16 v[82:97], v[154:157], v[106:109], v[82:97]
	v_mfma_f32_32x32x16_bf16 v[66:81], v[158:161], v[98:101], v[66:81]
	v_mfma_f32_32x32x16_bf16 v[82:97], v[158:161], v[102:105], v[82:97]
	s_waitcnt lgkmcnt(0)
	v_mfma_f32_32x32x16_bf16 v[50:65], v[134:137], v[210:213], v[50:65]
	v_mfma_f32_32x32x16_bf16 v[18:33], v[134:137], v[218:221], v[18:33]
	v_mfma_f32_32x32x16_bf16 v[34:49], v[130:133], v[210:213], v[34:49]
	v_mfma_f32_32x32x16_bf16 v[2:17], v[130:133], v[218:221], v[2:17]
	ds_read_b128 v[142:145], v175 offset:16384
	ds_read_b128 v[138:141], v175 offset:20480
	ds_read_b128 v[134:137], v176 offset:16384
	ds_read_b128 v[130:133], v176 offset:20480
	s_waitcnt vmcnt(0) lgkmcnt(0)
	s_setprio 0
	s_barrier
	v_exp_f32_e32 v66, v66
	v_exp_f32_e32 v67, v67
	v_exp_f32_e32 v68, v68
	v_exp_f32_e32 v69, v69
	v_exp_f32_e32 v82, v82
	v_exp_f32_e32 v83, v83
	v_exp_f32_e32 v84, v84
	v_exp_f32_e32 v85, v85
	v_exp_f32_e32 v70, v70
	v_exp_f32_e32 v71, v71
	v_exp_f32_e32 v72, v72
	v_exp_f32_e32 v73, v73
	v_exp_f32_e32 v86, v86
	v_exp_f32_e32 v87, v87
	v_exp_f32_e32 v88, v88
	v_exp_f32_e32 v89, v89
	v_exp_f32_e32 v74, v74
	v_exp_f32_e32 v75, v75
	v_exp_f32_e32 v76, v76
	v_exp_f32_e32 v77, v77
	v_exp_f32_e32 v90, v90
	v_exp_f32_e32 v91, v91
	v_exp_f32_e32 v92, v92
	v_exp_f32_e32 v93, v93
	v_exp_f32_e32 v78, v78
	v_exp_f32_e32 v79, v79
	v_exp_f32_e32 v80, v80
	v_exp_f32_e32 v81, v81
	v_exp_f32_e32 v94, v94
	v_exp_f32_e32 v95, v95
	v_exp_f32_e32 v96, v96
	v_exp_f32_e32 v97, v97
	v_add_f32_e32 v238, v82, v83
	v_add_f32_e32 v242, v66, v67
	v_add_f32_e32 v239, v84, v85
	v_add_f32_e32 v243, v68, v69
	v_add_f32_e32 v238, v238, v239
	v_add_f32_e32 v242, v242, v243
	v_add_f32_e32 v239, v86, v87
	v_add_f32_e32 v243, v70, v71
	v_add_f32_e32 v240, v88, v89
	v_add_f32_e32 v244, v72, v73
	v_add_f32_e32 v239, v239, v240
	v_add_f32_e32 v243, v243, v244
	v_add_f32_e32 v238, v238, v239
	v_add_f32_e32 v242, v242, v243
	v_add_f32_e32 v239, v90, v91
	v_add_f32_e32 v243, v74, v75
	v_add_f32_e32 v240, v92, v93
	v_add_f32_e32 v244, v76, v77
	v_add_f32_e32 v239, v239, v240
	v_add_f32_e32 v243, v243, v244
	v_add_f32_e32 v240, v94, v95
	v_add_f32_e32 v244, v78, v79
	v_add_f32_e32 v241, v96, v97
	v_add_f32_e32 v245, v80, v81
	v_add_f32_e32 v240, v240, v241
	v_add_f32_e32 v244, v244, v245
	v_add_f32_e32 v239, v239, v240
	v_add_f32_e32 v243, v243, v244
	v_add_f32_e32 v248, v238, v239
	v_add_f32_e32 v249, v242, v243
	v_cvt_pk_bf16_f32 v206, v82, v83
	v_cvt_pk_bf16_f32 v214, v66, v67
	v_cvt_pk_bf16_f32 v207, v84, v85
	v_cvt_pk_bf16_f32 v215, v68, v69
	v_cvt_pk_bf16_f32 v208, v86, v87
	v_cvt_pk_bf16_f32 v216, v70, v71
	v_cvt_pk_bf16_f32 v209, v88, v89
	v_cvt_pk_bf16_f32 v217, v72, v73
	v_cvt_pk_bf16_f32 v210, v90, v91
	v_cvt_pk_bf16_f32 v218, v74, v75
	v_cvt_pk_bf16_f32 v211, v92, v93
	v_cvt_pk_bf16_f32 v219, v76, v77
	v_cvt_pk_bf16_f32 v212, v94, v95
	v_cvt_pk_bf16_f32 v220, v78, v79
	v_cvt_pk_bf16_f32 v213, v96, v97
	v_cvt_pk_bf16_f32 v221, v80, v81
	s_barrier
; #define ATT_QK(S0_, S1_, kf_) do { \
;     _Pragma("unroll") for (int i_ = 0; i_ < 16; ++i_) { S0_[i_] = 0.f; S1_[i_] = 0.f; } \
;     _Pragma("unroll") for (int kk_ = 0; kk_ < 4; ++kk_) { \
;       S0_ = __builtin_amdgcn_mfma_f32_32x32x16_bf16(kf_[kk_], qf[0][kk_], S0_, 0, 0, 0); \
;       S1_ = __builtin_amdgcn_mfma_f32_32x32x16_bf16(kf_[kk_], qf[1][kk_], S1_, 0, 0, 0); } } while (0)
; #define ATT_PV(vf_, P0_, P1_) do { \
;     _Pragma("unroll") for (int c_ = 0; c_ < 2; ++c_) \
;     _Pragma("unroll") for (int db_ = 0; db_ < 2; ++db_) { \
;       O[db_][0] = __builtin_amdgcn_mfma_f32_32x32x16_bf16(vf_[db_ * 2 + c_], P0_[c_], O[db_][0], 0, 0, 0); \
;       O[db_][1] = __builtin_amdgcn_mfma_f32_32x32x16_bf16(vf_[db_ * 2 + c_], P1_[c_], O[db_][1], 0, 0, 0); } } while (0)
; #define WBAR() do { __builtin_amdgcn_sched_barrier(0); __builtin_amdgcn_s_barrier(); __builtin_amdgcn_sched_barrier(0); } while (0)
; __device__ __forceinline__ void attn_item_fast(const u16* __restrict__ Qg, const u16* __restrict__ Kg, const u16* __restrict__ Vtg,
;                                                u16* __restrict__ Og, const int L, char* smem, const int tid) {
;     ...
;   for (int t = 0; t < NT; ++t) {
;     const int cur = (t & 1) * 8192;
;     const char* Kb = Ks + cur; const char* Vb = Vs + cur;
;     if (t + 1 < NT) {
;       const char* kb_ = (const char*)Kg + (size_t)(t + 1) * (64 * 256 * 2);
;       const char* vb_ = (const char*)Vtg + (size_t)(t + 1) * 128;
;       glds16(koff, kb_, ldsK + (unsigned)(cur ^ 8192)); glds16(voff, vb_, ldsV + (unsigned)(cur ^ 8192));
;     }
;     ld_kf<0>(kf, Kb, r32, hi, sw);
;     ATT_PV(vf, P0, P1);
;     ld_vf<0>(vf, Vb, r32, hi, sw);
;     ATT_QK(S0, S1, kf);
;     ld_kf<1>(kf, Kb, r32, hi, sw);
;     WBAR();
;     exp_pack(S0, l0, P0[0], P0[1]); exp_pack(S1, l1, P1[0], P1[1]);
;     WBAR();
;     ATT_PV(vf, P0, P1);
;     ld_vf<1>(vf, Vb, r32, hi, sw);
;     ATT_QK(S0, S1, kf);
;     asm volatile("s_waitcnt vmcnt(0) lgkmcnt(0)" ::: "memory");
;     WBAR();
;     exp_pack(S0, l0, P0[0], P0[1]); exp_pack(S1, l1, P1[0], P1[1]);
;     WBAR();
;   }
;   if (half == 0) WBAR();
	s_setprio 1
	s_addk_i32 s53, 0x2000
	s_add_u32 s10, s10, 0x8000
	s_addc_u32 s11, s11, 0
	s_add_u32 s34, s34, 0x80
	s_addc_u32 s35, s35, 0
	s_cmp_eq_u32 s53, 0x3e000
	s_cbranch_scc0 .LBB0_102
	s_setprio 0
	v_add_f32_e32 v162, v162, v248
	v_add_f32_e32 v163, v163, v249
	v_mov_b32_e32 v74, v206
	v_mov_b32_e32 v75, v207
	v_mov_b32_e32 v76, v208
	v_mov_b32_e32 v77, v209
	v_mov_b32_e32 v70, v210
	v_mov_b32_e32 v71, v211
	v_mov_b32_e32 v72, v212
	v_mov_b32_e32 v73, v213
	v_mov_b32_e32 v78, v214
	v_mov_b32_e32 v79, v215
	v_mov_b32_e32 v80, v216
	v_mov_b32_e32 v81, v217
	v_mov_b32_e32 v66, v218
	v_mov_b32_e32 v67, v219
	v_mov_b32_e32 v68, v220
	v_mov_b32_e32 v69, v221
	v_add_u32_e32 v175, v170, v171
	ds_read_b128 v[146:149], v175 offset:8192
	s_waitcnt lgkmcnt(4)
	v_mfma_f32_32x32x16_bf16 v[50:65], v[142:145], v[74:77], v[50:65]
	v_add_u32_e32 v176, v170, v172
	ds_read_b128 v[150:153], v176 offset:8192
	v_add_u32_e32 v205, v170, v173
	ds_read_b128 v[154:157], v205 offset:8192
	v_add_u32_e32 v226, v170, v174
	ds_read_b128 v[158:161], v226 offset:8192
	ds_read_b128 v[178:181], v175 offset:24576
	ds_read_b128 v[182:185], v176 offset:24576
	ds_read_b128 v[186:189], v175 offset:28672
	ds_read_b128 v[206:209], v176 offset:28672
	v_mfma_f32_32x32x16_bf16 v[18:33], v[142:145], v[78:81], v[18:33]
	ds_read_b128 v[210:213], v175 offset:12288
	ds_read_b128 v[214:217], v176 offset:12288
	ds_read_b128 v[218:221], v205 offset:12288
	ds_read_b128 v[222:225], v226 offset:12288
	s_waitcnt lgkmcnt(14)
	v_mfma_f32_32x32x16_bf16 v[34:49], v[138:141], v[74:77], v[34:49]
	v_mfma_f32_32x32x16_bf16 v[2:17], v[138:141], v[78:81], v[2:17]
	s_waitcnt lgkmcnt(13)
	v_mfma_f32_32x32x16_bf16 v[50:65], v[134:137], v[70:73], v[50:65]
	v_mfma_f32_32x32x16_bf16 v[18:33], v[134:137], v[66:69], v[18:33]
	s_waitcnt lgkmcnt(12)
	v_mfma_f32_32x32x16_bf16 v[34:49], v[130:133], v[70:73], v[34:49]
	v_mfma_f32_32x32x16_bf16 v[2:17], v[130:133], v[66:69], v[2:17]
	s_waitcnt lgkmcnt(11)
	v_mfma_f32_32x32x16_bf16 v[82:97], v[146:149], v[118:121], 0
	v_mfma_f32_32x32x16_bf16 v[66:81], v[146:149], v[126:129], 0
	s_waitcnt lgkmcnt(10)
	v_mfma_f32_32x32x16_bf16 v[82:97], v[150:153], v[114:117], v[82:97]
	v_mfma_f32_32x32x16_bf16 v[66:81], v[150:153], v[122:125], v[66:81]
	s_waitcnt lgkmcnt(9)
	v_mfma_f32_32x32x16_bf16 v[82:97], v[154:157], v[106:109], v[82:97]
	v_mfma_f32_32x32x16_bf16 v[66:81], v[154:157], v[110:113], v[66:81]
	s_waitcnt lgkmcnt(8)
	v_mfma_f32_32x32x16_bf16 v[82:97], v[158:161], v[102:105], v[82:97]
	v_mfma_f32_32x32x16_bf16 v[66:81], v[158:161], v[98:101], v[66:81]
	s_barrier
	s_nop 9
	v_exp_f32_e32 v138, v82
	v_exp_f32_e32 v144, v83
	v_exp_f32_e32 v132, v84
	v_exp_f32_e32 v139, v85
	v_exp_f32_e32 v133, v86
	v_exp_f32_e32 v140, v87
	v_exp_f32_e32 v141, v88
	v_exp_f32_e32 v145, v89
	v_exp_f32_e32 v134, v90
	v_exp_f32_e32 v142, v91
	v_exp_f32_e32 v130, v92
	v_exp_f32_e32 v135, v93
	v_exp_f32_e32 v131, v94
	v_exp_f32_e32 v136, v95
	v_exp_f32_e32 v137, v96
	v_exp_f32_e32 v143, v97
	v_exp_f32_e32 v146, v66
	v_exp_f32_e32 v147, v67
	v_exp_f32_e32 v148, v68
	v_exp_f32_e32 v151, v69
	v_exp_f32_e32 v149, v70
	v_exp_f32_e32 v152, v71
	v_exp_f32_e32 v153, v72
	v_exp_f32_e32 v157, v73
	v_exp_f32_e32 v150, v74
	v_exp_f32_e32 v154, v75
	v_exp_f32_e32 v155, v76
	v_exp_f32_e32 v158, v77
	v_exp_f32_e32 v156, v78
	v_exp_f32_e32 v159, v79
	v_exp_f32_e32 v160, v80
	v_exp_f32_e32 v161, v81
	v_cvt_pk_bf16_f32 v82, v138, v144
	v_cvt_pk_bf16_f32 v83, v132, v139
	v_cvt_pk_bf16_f32 v84, v133, v140
	v_cvt_pk_bf16_f32 v85, v141, v145
	v_cvt_pk_bf16_f32 v86, v134, v142
	v_cvt_pk_bf16_f32 v87, v130, v135
	v_cvt_pk_bf16_f32 v88, v131, v136
	v_cvt_pk_bf16_f32 v89, v137, v143
	v_cvt_pk_bf16_f32 v66, v146, v147
	v_cvt_pk_bf16_f32 v67, v148, v151
	v_cvt_pk_bf16_f32 v68, v149, v152
	v_cvt_pk_bf16_f32 v69, v153, v157
	v_cvt_pk_bf16_f32 v70, v150, v154
	v_cvt_pk_bf16_f32 v71, v155, v158
	v_cvt_pk_bf16_f32 v72, v156, v159
	v_cvt_pk_bf16_f32 v73, v160, v161
	s_barrier
	s_waitcnt lgkmcnt(7)
	v_mfma_f32_32x32x16_bf16 v[50:65], v[178:181], v[82:85], v[50:65]
	v_mfma_f32_32x32x16_bf16 v[18:33], v[178:181], v[66:69], v[18:33]
	s_waitcnt lgkmcnt(5)
	v_mfma_f32_32x32x16_bf16 v[34:49], v[186:189], v[82:85], v[34:49]
	v_mfma_f32_32x32x16_bf16 v[2:17], v[186:189], v[66:69], v[2:17]
	v_mfma_f32_32x32x16_bf16 v[50:65], v[182:185], v[86:89], v[50:65]
	v_mfma_f32_32x32x16_bf16 v[18:33], v[182:185], v[70:73], v[18:33]
	s_waitcnt lgkmcnt(4)
	v_mfma_f32_32x32x16_bf16 v[34:49], v[206:209], v[86:89], v[34:49]
	v_mfma_f32_32x32x16_bf16 v[2:17], v[206:209], v[70:73], v[2:17]
	s_waitcnt lgkmcnt(3)
	v_mfma_f32_32x32x16_bf16 v[82:97], v[210:213], v[118:121], 0
	v_mfma_f32_32x32x16_bf16 v[66:81], v[210:213], v[126:129], 0
	s_waitcnt lgkmcnt(2)
	v_mfma_f32_32x32x16_bf16 v[82:97], v[214:217], v[114:117], v[82:97]
	v_mfma_f32_32x32x16_bf16 v[66:81], v[214:217], v[122:125], v[66:81]
	s_waitcnt lgkmcnt(1)
	v_mfma_f32_32x32x16_bf16 v[82:97], v[218:221], v[106:109], v[82:97]
	v_mfma_f32_32x32x16_bf16 v[66:81], v[218:221], v[110:113], v[66:81]
	s_waitcnt lgkmcnt(0)
	v_mfma_f32_32x32x16_bf16 v[82:97], v[222:225], v[102:105], v[82:97]
	ds_read_b128 v[114:117], v205 offset:24576
	ds_read_b128 v[110:113], v205 offset:28672
	ds_read_b128 v[106:109], v226 offset:24576
	ds_read_b128 v[102:105], v226 offset:28672
	s_waitcnt vmcnt(0) lgkmcnt(0)
	v_mfma_f32_32x32x16_bf16 v[66:81], v[222:225], v[98:101], v[66:81]
	s_barrier
	s_nop 5
	v_exp_f32_e32 v98, v82
	v_exp_f32_e32 v99, v83
	v_exp_f32_e32 v100, v84
	v_exp_f32_e32 v119, v85
	v_exp_f32_e32 v101, v86
	v_exp_f32_e32 v120, v87
	v_exp_f32_e32 v121, v88
	v_exp_f32_e32 v122, v89
	v_exp_f32_e32 v90, v90
	v_exp_f32_e32 v91, v91
	v_exp_f32_e32 v92, v92
	v_exp_f32_e32 v118, v93
	v_exp_f32_e32 v93, v94
	v_exp_f32_e32 v94, v95
	v_exp_f32_e32 v95, v96
	v_exp_f32_e32 v96, v97
	v_exp_f32_e32 v175, v66
	v_exp_f32_e32 v176, v67
	v_exp_f32_e32 v178, v68
	v_exp_f32_e32 v179, v69
	v_exp_f32_e32 v97, v70
	v_exp_f32_e32 v124, v71
	v_exp_f32_e32 v125, v72
	v_exp_f32_e32 v128, v73
	v_exp_f32_e32 v123, v74
	v_exp_f32_e32 v126, v75
	v_exp_f32_e32 v127, v76
	v_exp_f32_e32 v129, v77
	v_exp_f32_e32 v74, v78
	v_exp_f32_e32 v75, v79
	v_exp_f32_e32 v76, v80
	v_exp_f32_e32 v77, v81
	v_cvt_pk_bf16_f32 v86, v98, v99
	v_cvt_pk_bf16_f32 v87, v100, v119
	v_cvt_pk_bf16_f32 v88, v101, v120
	v_cvt_pk_bf16_f32 v89, v121, v122
	v_cvt_pk_bf16_f32 v82, v90, v91
	v_cvt_pk_bf16_f32 v83, v92, v118
	v_cvt_pk_bf16_f32 v84, v93, v94
	v_cvt_pk_bf16_f32 v85, v95, v96
	v_cvt_pk_bf16_f32 v70, v175, v176
	v_cvt_pk_bf16_f32 v71, v178, v179
	v_cvt_pk_bf16_f32 v72, v97, v124
	v_cvt_pk_bf16_f32 v73, v125, v128
	v_cvt_pk_bf16_f32 v66, v123, v126
	v_cvt_pk_bf16_f32 v67, v127, v129
	v_cvt_pk_bf16_f32 v68, v74, v75
	v_cvt_pk_bf16_f32 v69, v76, v77
	s_barrier
	s_cmpk_lt_u32 s14, 0x100
	s_cbranch_scc0 .LBB0_98
	s_barrier
	s_branch .LBB0_98
